# all six grid barriers: non-leader workgroups poll the global generation word directly (no per-XCD relay; split barriers B1/B2 no longer wait for the XCD leader's in-barrier work)
# speedup vs baseline: 1.0009x; 1.0009x over previous
.LBB0_172:
	s_mov_b32 s3, 0
	v_readlane_b32 s4, v251, 2
	v_readlane_b32 s5, v251, 3
	s_add_u32 s4, s4, s3
	s_addc_u32 s5, s5, 0
	s_waitcnt lgkmcnt(0)
	v_mov_b32_e32 v2, 0x3100
	s_add_u32 s6, s4, 0x3500
	s_addc_u32 s7, s5, 0
	global_load_dword v2, v2, s[4:5] offset:1024 sc1
	s_waitcnt vmcnt(0)
	v_cmp_ne_u32_e32 vcc, v2, v1
	s_cbranch_vccnz .LBB0_185
	s_add_u32 s4, s86, 0xf000200
	s_addc_u32 s5, s87, 0
	s_mov_b32 s3, 1
	v_mov_b32_e32 v2, 0
	s_branch .LBB0_175

.LBB0_623:
	s_mov_b32 s4, 0
	v_readlane_b32 s6, v251, 2
	v_readlane_b32 s7, v251, 3
	s_add_u32 s4, s6, s4
	s_addc_u32 s5, s7, 0
	s_waitcnt lgkmcnt(0)
	v_mov_b32_e32 v2, 0x3100
	global_load_dword v2, v2, s[4:5] offset:1024 sc1
	s_add_u32 s6, s4, 0x3500
	s_addc_u32 s7, s5, 0
	s_waitcnt vmcnt(0)
	v_cmp_ne_u32_e32 vcc, v2, v1
	s_cbranch_vccnz .LBB0_636
	s_add_u32 s4, s86, 0xf000200
	s_addc_u32 s5, s87, 0
	s_mov_b32 s14, 1
	v_mov_b32_e32 v2, 0
	s_branch .LBB0_626
